# v63 plus GEMM1 dilated-key epilogue: rotary waves load the table rows of row groups 1..5 together with group 0
# baseline (speedup 1.0000x reference)
.LBB0_318:
	v_lshlrev_b64 v[128:129], 6, v[172:173]
	v_lshl_add_u64 v[130:131], s[16:17], 0, v[128:129]
	v_lshlrev_b64 v[132:133], 2, v[168:169]
	v_lshl_add_u64 v[128:129], s[18:19], 0, v[128:129]
	v_lshl_add_u64 v[130:131], v[130:131], 0, v[132:133]
	v_lshl_add_u64 v[132:133], v[128:129], 0, v[132:133]
	global_load_dwordx4 v[128:131], v[130:131], off
	s_nop 0
	global_load_dwordx4 v[132:135], v[132:133], off
	v_lshlrev_b32_e32 v250, 6, v172
	v_lshl_add_u32 v250, v168, 2, v250
	v_add_u32_e32 v251, 0x2000, v250
	global_load_dwordx4 v[202:205], v250, s[16:17] offset:1024
	global_load_dwordx4 v[210:213], v250, s[18:19] offset:1024
	global_load_dwordx4 v[214:217], v250, s[16:17] offset:2048
	global_load_dwordx4 v[218:221], v250, s[18:19] offset:2048
	global_load_dwordx4 v[222:225], v250, s[16:17] offset:3072
	global_load_dwordx4 v[226:229], v250, s[18:19] offset:3072
	global_load_dwordx4 v[230:233], v251, s[16:17]
	global_load_dwordx4 v[234:237], v251, s[18:19]
	global_load_dwordx4 v[238:241], v251, s[16:17] offset:1024
	global_load_dwordx4 v[242:245], v251, s[18:19] offset:1024

.LBB0_339:
	v_lshlrev_b64 v[128:129], 6, v[176:177]
	v_lshl_add_u64 v[130:131], s[16:17], 0, v[128:129]
	v_lshlrev_b64 v[132:133], 2, v[168:169]
	v_lshl_add_u64 v[128:129], s[18:19], 0, v[128:129]
	v_lshl_add_u64 v[130:131], v[130:131], 0, v[132:133]
	v_lshl_add_u64 v[132:133], v[128:129], 0, v[132:133]
	v_mov_b32_e32 v128, v202
	v_mov_b32_e32 v129, v203
	v_mov_b32_e32 v130, v204
	v_mov_b32_e32 v131, v205
	v_mov_b32_e32 v132, v210
	v_mov_b32_e32 v133, v211
	v_mov_b32_e32 v134, v212
	v_mov_b32_e32 v135, v213

.LBB0_360:
	v_lshlrev_b64 v[128:129], 6, v[176:177]
	v_lshl_add_u64 v[130:131], s[16:17], 0, v[128:129]
	v_lshlrev_b64 v[132:133], 2, v[168:169]
	v_lshl_add_u64 v[128:129], s[18:19], 0, v[128:129]
	v_lshl_add_u64 v[130:131], v[130:131], 0, v[132:133]
	v_lshl_add_u64 v[132:133], v[128:129], 0, v[132:133]
	v_mov_b32_e32 v128, v214
	v_mov_b32_e32 v129, v215
	v_mov_b32_e32 v130, v216
	v_mov_b32_e32 v131, v217
	v_mov_b32_e32 v132, v218
	v_mov_b32_e32 v133, v219
	v_mov_b32_e32 v134, v220
	v_mov_b32_e32 v135, v221

.LBB0_381:
	v_lshlrev_b64 v[128:129], 6, v[176:177]
	v_lshl_add_u64 v[130:131], s[16:17], 0, v[128:129]
	v_lshlrev_b64 v[132:133], 2, v[168:169]
	v_lshl_add_u64 v[128:129], s[18:19], 0, v[128:129]
	v_lshl_add_u64 v[130:131], v[130:131], 0, v[132:133]
	v_lshl_add_u64 v[132:133], v[128:129], 0, v[132:133]
	v_mov_b32_e32 v128, v222
	v_mov_b32_e32 v129, v223
	v_mov_b32_e32 v130, v224
	v_mov_b32_e32 v131, v225
	v_mov_b32_e32 v132, v226
	v_mov_b32_e32 v133, v227
	v_mov_b32_e32 v134, v228
	v_mov_b32_e32 v135, v229

.LBB0_402:
	v_lshlrev_b64 v[128:129], 6, v[174:175]
	v_lshl_add_u64 v[130:131], s[16:17], 0, v[128:129]
	v_lshlrev_b64 v[132:133], 2, v[168:169]
	v_lshl_add_u64 v[128:129], s[18:19], 0, v[128:129]
	v_lshl_add_u64 v[130:131], v[130:131], 0, v[132:133]
	v_lshl_add_u64 v[132:133], v[128:129], 0, v[132:133]
	v_mov_b32_e32 v128, v230
	v_mov_b32_e32 v129, v231
	v_mov_b32_e32 v130, v232
	v_mov_b32_e32 v131, v233
	v_mov_b32_e32 v132, v234
	v_mov_b32_e32 v133, v235
	v_mov_b32_e32 v134, v236
	v_mov_b32_e32 v135, v237

.LBB0_423:
	v_lshlrev_b64 v[128:129], 6, v[174:175]
	v_lshl_add_u64 v[130:131], s[16:17], 0, v[128:129]
	v_lshlrev_b64 v[132:133], 2, v[168:169]
	v_lshl_add_u64 v[128:129], s[18:19], 0, v[128:129]
	v_lshl_add_u64 v[130:131], v[130:131], 0, v[132:133]
	v_lshl_add_u64 v[132:133], v[128:129], 0, v[132:133]
	v_mov_b32_e32 v128, v238
	v_mov_b32_e32 v129, v239
	v_mov_b32_e32 v130, v240
	v_mov_b32_e32 v131, v241
	v_mov_b32_e32 v132, v242
	v_mov_b32_e32 v133, v243
	v_mov_b32_e32 v134, v244
	v_mov_b32_e32 v135, v245
